# input-projection GEMM phase: stagger sweep point s_sleep 16
# baseline (speedup 1.0000x reference)
.LBB0_277:
	s_or_b64 exec, exec, s[0:1]
	s_and_b32 s0, s33, 1
	s_bitcmp1_b32 s33, 0
	s_cselect_b64 s[2:3], -1, 0
	v_writelane_b32 v246, s2, 26
	s_cmp_eq_u32 s0, 0
	s_waitcnt lgkmcnt(0)
	s_barrier
	v_writelane_b32 v246, s3, 27
	s_cbranch_scc1 .LBB0_279
	s_sleep 16
